# trim1 + rstd_rows fast path: 4 rows per group, two register sets software pipelined (taken when grid*8 == 2048 waves)
# speedup vs baseline: 1.0018x; 1.0018x over previous
; __device__ __forceinline__ void rstd_rows(const bf16_t* __restrict__ Hb, float* __restrict__ rs, int nrows, int gw, int NGW, int lane) {
;     for (int m = gw; m < nrows; m += 2 * NGW) {
;         const int m2 = m + NGW; const bool has2 = m2 < nrows;
;         const u32x4* p0 = (const u32x4*)(Hb + (size_t)m * DMODEL) + lane; const u32x4* p1 = (const u32x4*)(Hb + (size_t)(has2 ? m2 : m) * DMODEL) + lane;
;         const u32x4 a0 = p0[0], a1 = p0[64], b0 = p1[0], b1 = p1[64];
;         float s0 = 0.f, s1 = 0.f;
; #pragma unroll
;         for (int k = 0; k < 4; ++k) { float x, y;
;             x = __uint_as_float(a0[k] << 16); y = __uint_as_float(a0[k] & 0xffff0000u); s0 += x * x + y * y;
;             x = __uint_as_float(a1[k] << 16); y = __uint_as_float(a1[k] & 0xffff0000u); s0 += x * x + y * y;
;             x = __uint_as_float(b0[k] << 16); y = __uint_as_float(b0[k] & 0xffff0000u); s1 += x * x + y * y;
;             x = __uint_as_float(b1[k] << 16); y = __uint_as_float(b1[k] & 0xffff0000u); s1 += x * x + y * y; }
;         s0 = wave_sum(s0); s1 = wave_sum(s1);
;         if (lane == 0) { rs[m] = rsqrtf(s0 * (1.0f / DMODEL) + EPS); if (has2) rs[m2] = rsqrtf(s1 * (1.0f / DMODEL) + EPS); }
;     }
; }
.LBB0_388:
	s_nop 0
	v_readlane_b32 s4, v252, 34
	v_readlane_b32 s5, v252, 35
	v_readlane_b32 s34, v252, 11
	v_readlane_b32 s38, v252, 29
	s_andn2_b64 vcc, exec, s[4:5]
	v_readlane_b32 s35, v252, 12
	v_readlane_b32 s39, v252, 30
	v_readlane_b32 s57, v252, 10
	s_cbranch_vccnz .LBB0_396
	s_cmp_eq_u32 s59, 0
	s_cselect_b64 s[4:5], -1, 0
	s_cmp_lt_i32 s38, 14
	s_cselect_b64 s[6:7], -1, 0
	v_mbcnt_lo_u32_b32 v0, -1, 0
	v_mbcnt_hi_u32_b32 v0, -1, v0
	s_and_b64 s[4:5], s[6:7], s[4:5]
	v_add_u32_e32 v0, s33, v0
	s_and_b64 vcc, exec, s[4:5]
	s_cbranch_vccnz .LBB0_396
	s_lshl_b32 s0, s62, 3
	s_add_i32 s8, s0, s57
	s_cmp_gt_i32 s8, 0x13fff
	s_cbranch_scc1 .LBB0_396
	v_readlane_b32 s4, v252, 21
	v_readlane_b32 s6, v252, 23
	v_readlane_b32 s7, v252, 24
	s_add_u32 s0, s6, 0x300000
	v_and_b32_e32 v4, 63, v0
	v_readlane_b32 s5, v252, 22
	s_addc_u32 s13, s7, 0
	v_lshlrev_b32_e32 v0, 4, v4
	s_ashr_i32 s55, s54, 31
	v_lshl_add_u64 v[2:3], s[60:61], 0, v[0:1]
	v_cmp_eq_u32_e64 s[6:7], 0, v4
	s_lshl_b64 s[4:5], s[54:55], 2
	s_cmpk_lg_i32 s54, 0x800
	s_cbranch_scc1 .LBB0_393
	s_mov_b32 s100, 0x400000
	s_mov_b32 s101, 0
	s_lshl_b32 s10, s8, 11
	s_mov_b32 s11, 0
	v_lshl_add_u64 v[28:29], v[2:3], 0, s[10:11]
	global_load_dwordx4 v[4:7], v[28:29], off
	global_load_dwordx4 v[8:11], v[28:29], off offset:1024
	v_lshl_add_u64 v[38:39], v[28:29], 0, s[100:101]
	global_load_dwordx4 v[12:15], v[38:39], off
	global_load_dwordx4 v[16:19], v[38:39], off offset:1024
	v_lshl_add_u64 v[28:29], v[38:39], 0, s[100:101]
	global_load_dwordx4 v[20:23], v[28:29], off
	global_load_dwordx4 v[24:27], v[28:29], off offset:1024
	v_lshl_add_u64 v[38:39], v[28:29], 0, s[100:101]
	global_load_dwordx4 v[30:33], v[38:39], off
	global_load_dwordx4 v[34:37], v[38:39], off offset:1024
.Lrs4_loop:
	s_add_i32 s16, s8, 0x2000
	s_lshl_b32 s10, s16, 11
	s_mov_b32 s11, 0
	v_lshl_add_u64 v[28:29], v[2:3], 0, s[10:11]
	global_load_dwordx4 v[48:51], v[28:29], off
	global_load_dwordx4 v[52:55], v[28:29], off offset:1024
	v_lshl_add_u64 v[38:39], v[28:29], 0, s[100:101]
	global_load_dwordx4 v[56:59], v[38:39], off
	global_load_dwordx4 v[60:63], v[38:39], off offset:1024
	v_lshl_add_u64 v[28:29], v[38:39], 0, s[100:101]
	global_load_dwordx4 v[64:67], v[28:29], off
	global_load_dwordx4 v[68:71], v[28:29], off offset:1024
	v_lshl_add_u64 v[38:39], v[28:29], 0, s[100:101]
	global_load_dwordx4 v[72:75], v[38:39], off
	global_load_dwordx4 v[76:79], v[38:39], off offset:1024
	s_waitcnt vmcnt(14)
	v_lshlrev_b32_e32 v44, 16, v4
	v_and_b32_e32 v4, 0xffff0000, v4
	v_mul_f32_e32 v40, v44, v44
	v_fmac_f32_e32 v40, v4, v4
	v_lshlrev_b32_e32 v44, 16, v5
	v_and_b32_e32 v5, 0xffff0000, v5
	v_fmac_f32_e32 v40, v44, v44
	v_fmac_f32_e32 v40, v5, v5
	v_lshlrev_b32_e32 v44, 16, v6
	v_and_b32_e32 v6, 0xffff0000, v6
	v_fmac_f32_e32 v40, v44, v44
	v_fmac_f32_e32 v40, v6, v6
	v_lshlrev_b32_e32 v44, 16, v7
	v_and_b32_e32 v7, 0xffff0000, v7
	v_fmac_f32_e32 v40, v44, v44
	v_fmac_f32_e32 v40, v7, v7
	v_lshlrev_b32_e32 v44, 16, v8
	v_and_b32_e32 v8, 0xffff0000, v8
	v_fmac_f32_e32 v40, v44, v44
	v_fmac_f32_e32 v40, v8, v8
	v_lshlrev_b32_e32 v44, 16, v9
	v_and_b32_e32 v9, 0xffff0000, v9
	v_fmac_f32_e32 v40, v44, v44
	v_fmac_f32_e32 v40, v9, v9
	v_lshlrev_b32_e32 v44, 16, v10
	v_and_b32_e32 v10, 0xffff0000, v10
	v_fmac_f32_e32 v40, v44, v44
	v_fmac_f32_e32 v40, v10, v10
	v_lshlrev_b32_e32 v44, 16, v11
	v_and_b32_e32 v11, 0xffff0000, v11
	v_fmac_f32_e32 v40, v44, v44
	v_fmac_f32_e32 v40, v11, v11
	s_waitcnt vmcnt(12)
	v_lshlrev_b32_e32 v44, 16, v12
	v_and_b32_e32 v12, 0xffff0000, v12
	v_mul_f32_e32 v41, v44, v44
	v_fmac_f32_e32 v41, v12, v12
	v_lshlrev_b32_e32 v44, 16, v13
	v_and_b32_e32 v13, 0xffff0000, v13
	v_fmac_f32_e32 v41, v44, v44
	v_fmac_f32_e32 v41, v13, v13
	v_lshlrev_b32_e32 v44, 16, v14
	v_and_b32_e32 v14, 0xffff0000, v14
	v_fmac_f32_e32 v41, v44, v44
	v_fmac_f32_e32 v41, v14, v14
	v_lshlrev_b32_e32 v44, 16, v15
	v_and_b32_e32 v15, 0xffff0000, v15
	v_fmac_f32_e32 v41, v44, v44
	v_fmac_f32_e32 v41, v15, v15
	v_lshlrev_b32_e32 v44, 16, v16
	v_and_b32_e32 v16, 0xffff0000, v16
	v_fmac_f32_e32 v41, v44, v44
	v_fmac_f32_e32 v41, v16, v16
	v_lshlrev_b32_e32 v44, 16, v17
	v_and_b32_e32 v17, 0xffff0000, v17
	v_fmac_f32_e32 v41, v44, v44
	v_fmac_f32_e32 v41, v17, v17
	v_lshlrev_b32_e32 v44, 16, v18
	v_and_b32_e32 v18, 0xffff0000, v18
	v_fmac_f32_e32 v41, v44, v44
	v_fmac_f32_e32 v41, v18, v18
	v_lshlrev_b32_e32 v44, 16, v19
	v_and_b32_e32 v19, 0xffff0000, v19
	v_fmac_f32_e32 v41, v44, v44
	v_fmac_f32_e32 v41, v19, v19
	s_waitcnt vmcnt(10)
	v_lshlrev_b32_e32 v44, 16, v20
	v_and_b32_e32 v20, 0xffff0000, v20
	v_mul_f32_e32 v42, v44, v44
	v_fmac_f32_e32 v42, v20, v20
	v_lshlrev_b32_e32 v44, 16, v21
	v_and_b32_e32 v21, 0xffff0000, v21
	v_fmac_f32_e32 v42, v44, v44
	v_fmac_f32_e32 v42, v21, v21
	v_lshlrev_b32_e32 v44, 16, v22
	v_and_b32_e32 v22, 0xffff0000, v22
	v_fmac_f32_e32 v42, v44, v44
	v_fmac_f32_e32 v42, v22, v22
	v_lshlrev_b32_e32 v44, 16, v23
	v_and_b32_e32 v23, 0xffff0000, v23
	v_fmac_f32_e32 v42, v44, v44
	v_fmac_f32_e32 v42, v23, v23
	v_lshlrev_b32_e32 v44, 16, v24
	v_and_b32_e32 v24, 0xffff0000, v24
	v_fmac_f32_e32 v42, v44, v44
	v_fmac_f32_e32 v42, v24, v24
	v_lshlrev_b32_e32 v44, 16, v25
	v_and_b32_e32 v25, 0xffff0000, v25
	v_fmac_f32_e32 v42, v44, v44
	v_fmac_f32_e32 v42, v25, v25
	v_lshlrev_b32_e32 v44, 16, v26
	v_and_b32_e32 v26, 0xffff0000, v26
	v_fmac_f32_e32 v42, v44, v44
	v_fmac_f32_e32 v42, v26, v26
	v_lshlrev_b32_e32 v44, 16, v27
	v_and_b32_e32 v27, 0xffff0000, v27
	v_fmac_f32_e32 v42, v44, v44
	v_fmac_f32_e32 v42, v27, v27
	s_waitcnt vmcnt(8)
; __device__ __forceinline__ void rstd_rows(const bf16_t* __restrict__ Hb, float* __restrict__ rs, int nrows, int gw, int NGW, int lane) {
;     for (int m = gw; m < nrows; m += 2 * NGW) {
;         const int m2 = m + NGW; const bool has2 = m2 < nrows;
;         const u32x4* p0 = (const u32x4*)(Hb + (size_t)m * DMODEL) + lane; const u32x4* p1 = (const u32x4*)(Hb + (size_t)(has2 ? m2 : m) * DMODEL) + lane;
;         const u32x4 a0 = p0[0], a1 = p0[64], b0 = p1[0], b1 = p1[64];
;         float s0 = 0.f, s1 = 0.f;
; #pragma unroll
;         for (int k = 0; k < 4; ++k) { float x, y;
;             x = __uint_as_float(a0[k] << 16); y = __uint_as_float(a0[k] & 0xffff0000u); s0 += x * x + y * y;
;             x = __uint_as_float(a1[k] << 16); y = __uint_as_float(a1[k] & 0xffff0000u); s0 += x * x + y * y;
;             x = __uint_as_float(b0[k] << 16); y = __uint_as_float(b0[k] & 0xffff0000u); s1 += x * x + y * y;
;             x = __uint_as_float(b1[k] << 16); y = __uint_as_float(b1[k] & 0xffff0000u); s1 += x * x + y * y; }
;         s0 = wave_sum(s0); s1 = wave_sum(s1);
;         if (lane == 0) { rs[m] = rsqrtf(s0 * (1.0f / DMODEL) + EPS); if (has2) rs[m2] = rsqrtf(s1 * (1.0f / DMODEL) + EPS); }
;     }
; }
	v_lshlrev_b32_e32 v44, 16, v30
	v_and_b32_e32 v30, 0xffff0000, v30
	v_mul_f32_e32 v43, v44, v44
	v_fmac_f32_e32 v43, v30, v30
	v_lshlrev_b32_e32 v44, 16, v31
	v_and_b32_e32 v31, 0xffff0000, v31
	v_fmac_f32_e32 v43, v44, v44
	v_fmac_f32_e32 v43, v31, v31
	v_lshlrev_b32_e32 v44, 16, v32
	v_and_b32_e32 v32, 0xffff0000, v32
	v_fmac_f32_e32 v43, v44, v44
	v_fmac_f32_e32 v43, v32, v32
	v_lshlrev_b32_e32 v44, 16, v33
	v_and_b32_e32 v33, 0xffff0000, v33
	v_fmac_f32_e32 v43, v44, v44
	v_fmac_f32_e32 v43, v33, v33
	v_lshlrev_b32_e32 v44, 16, v34
	v_and_b32_e32 v34, 0xffff0000, v34
	v_fmac_f32_e32 v43, v44, v44
	v_fmac_f32_e32 v43, v34, v34
	v_lshlrev_b32_e32 v44, 16, v35
	v_and_b32_e32 v35, 0xffff0000, v35
	v_fmac_f32_e32 v43, v44, v44
	v_fmac_f32_e32 v43, v35, v35
	v_lshlrev_b32_e32 v44, 16, v36
	v_and_b32_e32 v36, 0xffff0000, v36
	v_fmac_f32_e32 v43, v44, v44
	v_fmac_f32_e32 v43, v36, v36
	v_lshlrev_b32_e32 v44, 16, v37
	v_and_b32_e32 v37, 0xffff0000, v37
	v_fmac_f32_e32 v43, v44, v44
	v_fmac_f32_e32 v43, v37, v37
	ds_swizzle_b32 v44, v40 offset:swizzle(SWAP,1)
	ds_swizzle_b32 v45, v41 offset:swizzle(SWAP,1)
	ds_swizzle_b32 v46, v42 offset:swizzle(SWAP,1)
	ds_swizzle_b32 v47, v43 offset:swizzle(SWAP,1)
	s_waitcnt lgkmcnt(3)
	v_add_f32_e32 v40, v40, v44
	s_waitcnt lgkmcnt(2)
	v_add_f32_e32 v41, v41, v45
	s_waitcnt lgkmcnt(1)
	v_add_f32_e32 v42, v42, v46
	s_waitcnt lgkmcnt(0)
	v_add_f32_e32 v43, v43, v47
	ds_swizzle_b32 v44, v40 offset:swizzle(SWAP,2)
	ds_swizzle_b32 v45, v41 offset:swizzle(SWAP,2)
	ds_swizzle_b32 v46, v42 offset:swizzle(SWAP,2)
	ds_swizzle_b32 v47, v43 offset:swizzle(SWAP,2)
	s_waitcnt lgkmcnt(3)
	v_add_f32_e32 v40, v40, v44
	s_waitcnt lgkmcnt(2)
	v_add_f32_e32 v41, v41, v45
	s_waitcnt lgkmcnt(1)
	v_add_f32_e32 v42, v42, v46
	s_waitcnt lgkmcnt(0)
	v_add_f32_e32 v43, v43, v47
	ds_swizzle_b32 v44, v40 offset:swizzle(SWAP,4)
	ds_swizzle_b32 v45, v41 offset:swizzle(SWAP,4)
	ds_swizzle_b32 v46, v42 offset:swizzle(SWAP,4)
	ds_swizzle_b32 v47, v43 offset:swizzle(SWAP,4)
	s_waitcnt lgkmcnt(3)
	v_add_f32_e32 v40, v40, v44
	s_waitcnt lgkmcnt(2)
	v_add_f32_e32 v41, v41, v45
	s_waitcnt lgkmcnt(1)
	v_add_f32_e32 v42, v42, v46
	s_waitcnt lgkmcnt(0)
	v_add_f32_e32 v43, v43, v47
	ds_swizzle_b32 v44, v40 offset:swizzle(SWAP,8)
	ds_swizzle_b32 v45, v41 offset:swizzle(SWAP,8)
	ds_swizzle_b32 v46, v42 offset:swizzle(SWAP,8)
	ds_swizzle_b32 v47, v43 offset:swizzle(SWAP,8)
	s_waitcnt lgkmcnt(3)
	v_add_f32_e32 v40, v40, v44
	s_waitcnt lgkmcnt(2)
	v_add_f32_e32 v41, v41, v45
	s_waitcnt lgkmcnt(1)
	v_add_f32_e32 v42, v42, v46
	s_waitcnt lgkmcnt(0)
	v_add_f32_e32 v43, v43, v47
	ds_swizzle_b32 v44, v40 offset:swizzle(SWAP,16)
	ds_swizzle_b32 v45, v41 offset:swizzle(SWAP,16)
	ds_swizzle_b32 v46, v42 offset:swizzle(SWAP,16)
	ds_swizzle_b32 v47, v43 offset:swizzle(SWAP,16)
	s_waitcnt lgkmcnt(3)
	v_add_f32_e32 v40, v40, v44
	s_waitcnt lgkmcnt(2)
	v_add_f32_e32 v41, v41, v45
	s_waitcnt lgkmcnt(1)
	v_add_f32_e32 v42, v42, v46
	s_waitcnt lgkmcnt(0)
	v_add_f32_e32 v43, v43, v47
	v_mov_b32_e32 v44, v40
	v_mov_b32_e32 v45, v41
	v_mov_b32_e32 v46, v42
	v_mov_b32_e32 v47, v43
	s_nop 1
	v_permlane32_swap_b32_e32 v40, v44
	v_permlane32_swap_b32_e32 v41, v45
	v_permlane32_swap_b32_e32 v42, v46
	v_permlane32_swap_b32_e32 v43, v47
	s_and_saveexec_b64 s[14:15], s[6:7]
	v_add_f32_e32 v40, v40, v44
	v_add_f32_e32 v41, v41, v45
	v_add_f32_e32 v42, v42, v46
	v_add_f32_e32 v43, v43, v47
	v_fmamk_f32 v40, v40, 0x3a800000, v200
	v_fmamk_f32 v41, v41, 0x3a800000, v200
	v_fmamk_f32 v42, v42, 0x3a800000, v200
	v_fmamk_f32 v43, v43, 0x3a800000, v200
	v_rsq_f32_e32 v40, v40
	v_rsq_f32_e32 v41, v41
	v_rsq_f32_e32 v42, v42
	v_rsq_f32_e32 v43, v43
	s_lshl_b32 s10, s8, 2
	s_add_u32 s10, s0, s10
	s_addc_u32 s11, s13, 0
	global_store_dword v1, v40, s[10:11]
	s_add_u32 s10, s10, 0x2000
	s_addc_u32 s11, s11, 0
	global_store_dword v1, v41, s[10:11]
	s_add_u32 s10, s10, 0x2000
	s_addc_u32 s11, s11, 0
	global_store_dword v1, v42, s[10:11]
	s_add_u32 s10, s10, 0x2000
	s_addc_u32 s11, s11, 0
	global_store_dword v1, v43, s[10:11]
	s_or_b64 exec, exec, s[14:15]
	s_add_i32 s16, s8, 0x4000
	s_lshl_b32 s10, s16, 11
	s_mov_b32 s11, 0
	v_lshl_add_u64 v[28:29], v[2:3], 0, s[10:11]
	global_load_dwordx4 v[4:7], v[28:29], off
	global_load_dwordx4 v[8:11], v[28:29], off offset:1024
	v_lshl_add_u64 v[38:39], v[28:29], 0, s[100:101]
	global_load_dwordx4 v[12:15], v[38:39], off
	global_load_dwordx4 v[16:19], v[38:39], off offset:1024
	v_lshl_add_u64 v[28:29], v[38:39], 0, s[100:101]
	global_load_dwordx4 v[20:23], v[28:29], off
	global_load_dwordx4 v[24:27], v[28:29], off offset:1024
	v_lshl_add_u64 v[38:39], v[28:29], 0, s[100:101]
	global_load_dwordx4 v[30:33], v[38:39], off
	global_load_dwordx4 v[34:37], v[38:39], off offset:1024
	s_addk_i32 s8, 0x2000
	s_waitcnt vmcnt(14)
	v_lshlrev_b32_e32 v44, 16, v48
	v_and_b32_e32 v48, 0xffff0000, v48
	v_mul_f32_e32 v40, v44, v44
	v_fmac_f32_e32 v40, v48, v48
	v_lshlrev_b32_e32 v44, 16, v49
	v_and_b32_e32 v49, 0xffff0000, v49
	v_fmac_f32_e32 v40, v44, v44
	v_fmac_f32_e32 v40, v49, v49
	v_lshlrev_b32_e32 v44, 16, v50
	v_and_b32_e32 v50, 0xffff0000, v50
	v_fmac_f32_e32 v40, v44, v44
	v_fmac_f32_e32 v40, v50, v50
	v_lshlrev_b32_e32 v44, 16, v51
	v_and_b32_e32 v51, 0xffff0000, v51
	v_fmac_f32_e32 v40, v44, v44
	v_fmac_f32_e32 v40, v51, v51
	v_lshlrev_b32_e32 v44, 16, v52
	v_and_b32_e32 v52, 0xffff0000, v52
	v_fmac_f32_e32 v40, v44, v44
	v_fmac_f32_e32 v40, v52, v52
	v_lshlrev_b32_e32 v44, 16, v53
	v_and_b32_e32 v53, 0xffff0000, v53
	v_fmac_f32_e32 v40, v44, v44
	v_fmac_f32_e32 v40, v53, v53
	v_lshlrev_b32_e32 v44, 16, v54
	v_and_b32_e32 v54, 0xffff0000, v54
	v_fmac_f32_e32 v40, v44, v44
	v_fmac_f32_e32 v40, v54, v54
	v_lshlrev_b32_e32 v44, 16, v55
	v_and_b32_e32 v55, 0xffff0000, v55
	v_fmac_f32_e32 v40, v44, v44
	v_fmac_f32_e32 v40, v55, v55
	s_waitcnt vmcnt(12)
; __device__ __forceinline__ void rstd_rows(const bf16_t* __restrict__ Hb, float* __restrict__ rs, int nrows, int gw, int NGW, int lane) {
;     for (int m = gw; m < nrows; m += 2 * NGW) {
;         const int m2 = m + NGW; const bool has2 = m2 < nrows;
;         const u32x4* p0 = (const u32x4*)(Hb + (size_t)m * DMODEL) + lane; const u32x4* p1 = (const u32x4*)(Hb + (size_t)(has2 ? m2 : m) * DMODEL) + lane;
;         const u32x4 a0 = p0[0], a1 = p0[64], b0 = p1[0], b1 = p1[64];
;         float s0 = 0.f, s1 = 0.f;
; #pragma unroll
;         for (int k = 0; k < 4; ++k) { float x, y;
;             x = __uint_as_float(a0[k] << 16); y = __uint_as_float(a0[k] & 0xffff0000u); s0 += x * x + y * y;
;             x = __uint_as_float(a1[k] << 16); y = __uint_as_float(a1[k] & 0xffff0000u); s0 += x * x + y * y;
;             x = __uint_as_float(b0[k] << 16); y = __uint_as_float(b0[k] & 0xffff0000u); s1 += x * x + y * y;
;             x = __uint_as_float(b1[k] << 16); y = __uint_as_float(b1[k] & 0xffff0000u); s1 += x * x + y * y; }
;         s0 = wave_sum(s0); s1 = wave_sum(s1);
;         if (lane == 0) { rs[m] = rsqrtf(s0 * (1.0f / DMODEL) + EPS); if (has2) rs[m2] = rsqrtf(s1 * (1.0f / DMODEL) + EPS); }
;     }
; }
	v_lshlrev_b32_e32 v44, 16, v56
	v_and_b32_e32 v56, 0xffff0000, v56
	v_mul_f32_e32 v41, v44, v44
	v_fmac_f32_e32 v41, v56, v56
	v_lshlrev_b32_e32 v44, 16, v57
	v_and_b32_e32 v57, 0xffff0000, v57
	v_fmac_f32_e32 v41, v44, v44
	v_fmac_f32_e32 v41, v57, v57
	v_lshlrev_b32_e32 v44, 16, v58
	v_and_b32_e32 v58, 0xffff0000, v58
	v_fmac_f32_e32 v41, v44, v44
	v_fmac_f32_e32 v41, v58, v58
	v_lshlrev_b32_e32 v44, 16, v59
	v_and_b32_e32 v59, 0xffff0000, v59
	v_fmac_f32_e32 v41, v44, v44
	v_fmac_f32_e32 v41, v59, v59
	v_lshlrev_b32_e32 v44, 16, v60
	v_and_b32_e32 v60, 0xffff0000, v60
	v_fmac_f32_e32 v41, v44, v44
	v_fmac_f32_e32 v41, v60, v60
	v_lshlrev_b32_e32 v44, 16, v61
	v_and_b32_e32 v61, 0xffff0000, v61
	v_fmac_f32_e32 v41, v44, v44
	v_fmac_f32_e32 v41, v61, v61
	v_lshlrev_b32_e32 v44, 16, v62
	v_and_b32_e32 v62, 0xffff0000, v62
	v_fmac_f32_e32 v41, v44, v44
	v_fmac_f32_e32 v41, v62, v62
	v_lshlrev_b32_e32 v44, 16, v63
	v_and_b32_e32 v63, 0xffff0000, v63
	v_fmac_f32_e32 v41, v44, v44
	v_fmac_f32_e32 v41, v63, v63
	s_waitcnt vmcnt(10)
	v_lshlrev_b32_e32 v44, 16, v64
	v_and_b32_e32 v64, 0xffff0000, v64
	v_mul_f32_e32 v42, v44, v44
	v_fmac_f32_e32 v42, v64, v64
	v_lshlrev_b32_e32 v44, 16, v65
	v_and_b32_e32 v65, 0xffff0000, v65
	v_fmac_f32_e32 v42, v44, v44
	v_fmac_f32_e32 v42, v65, v65
	v_lshlrev_b32_e32 v44, 16, v66
	v_and_b32_e32 v66, 0xffff0000, v66
	v_fmac_f32_e32 v42, v44, v44
	v_fmac_f32_e32 v42, v66, v66
	v_lshlrev_b32_e32 v44, 16, v67
	v_and_b32_e32 v67, 0xffff0000, v67
	v_fmac_f32_e32 v42, v44, v44
	v_fmac_f32_e32 v42, v67, v67
	v_lshlrev_b32_e32 v44, 16, v68
	v_and_b32_e32 v68, 0xffff0000, v68
	v_fmac_f32_e32 v42, v44, v44
	v_fmac_f32_e32 v42, v68, v68
	v_lshlrev_b32_e32 v44, 16, v69
	v_and_b32_e32 v69, 0xffff0000, v69
	v_fmac_f32_e32 v42, v44, v44
	v_fmac_f32_e32 v42, v69, v69
	v_lshlrev_b32_e32 v44, 16, v70
	v_and_b32_e32 v70, 0xffff0000, v70
	v_fmac_f32_e32 v42, v44, v44
	v_fmac_f32_e32 v42, v70, v70
	v_lshlrev_b32_e32 v44, 16, v71
	v_and_b32_e32 v71, 0xffff0000, v71
	v_fmac_f32_e32 v42, v44, v44
	v_fmac_f32_e32 v42, v71, v71
	s_waitcnt vmcnt(8)
	v_lshlrev_b32_e32 v44, 16, v72
	v_and_b32_e32 v72, 0xffff0000, v72
	v_mul_f32_e32 v43, v44, v44
	v_fmac_f32_e32 v43, v72, v72
	v_lshlrev_b32_e32 v44, 16, v73
	v_and_b32_e32 v73, 0xffff0000, v73
	v_fmac_f32_e32 v43, v44, v44
	v_fmac_f32_e32 v43, v73, v73
	v_lshlrev_b32_e32 v44, 16, v74
	v_and_b32_e32 v74, 0xffff0000, v74
	v_fmac_f32_e32 v43, v44, v44
	v_fmac_f32_e32 v43, v74, v74
	v_lshlrev_b32_e32 v44, 16, v75
	v_and_b32_e32 v75, 0xffff0000, v75
	v_fmac_f32_e32 v43, v44, v44
	v_fmac_f32_e32 v43, v75, v75
	v_lshlrev_b32_e32 v44, 16, v76
	v_and_b32_e32 v76, 0xffff0000, v76
	v_fmac_f32_e32 v43, v44, v44
	v_fmac_f32_e32 v43, v76, v76
	v_lshlrev_b32_e32 v44, 16, v77
	v_and_b32_e32 v77, 0xffff0000, v77
	v_fmac_f32_e32 v43, v44, v44
	v_fmac_f32_e32 v43, v77, v77
	v_lshlrev_b32_e32 v44, 16, v78
	v_and_b32_e32 v78, 0xffff0000, v78
	v_fmac_f32_e32 v43, v44, v44
	v_fmac_f32_e32 v43, v78, v78
	v_lshlrev_b32_e32 v44, 16, v79
	v_and_b32_e32 v79, 0xffff0000, v79
	v_fmac_f32_e32 v43, v44, v44
	v_fmac_f32_e32 v43, v79, v79
	ds_swizzle_b32 v44, v40 offset:swizzle(SWAP,1)
	ds_swizzle_b32 v45, v41 offset:swizzle(SWAP,1)
	ds_swizzle_b32 v46, v42 offset:swizzle(SWAP,1)
	ds_swizzle_b32 v47, v43 offset:swizzle(SWAP,1)
	s_waitcnt lgkmcnt(3)
	v_add_f32_e32 v40, v40, v44
	s_waitcnt lgkmcnt(2)
	v_add_f32_e32 v41, v41, v45
	s_waitcnt lgkmcnt(1)
	v_add_f32_e32 v42, v42, v46
	s_waitcnt lgkmcnt(0)
	v_add_f32_e32 v43, v43, v47
	ds_swizzle_b32 v44, v40 offset:swizzle(SWAP,2)
	ds_swizzle_b32 v45, v41 offset:swizzle(SWAP,2)
	ds_swizzle_b32 v46, v42 offset:swizzle(SWAP,2)
	ds_swizzle_b32 v47, v43 offset:swizzle(SWAP,2)
	s_waitcnt lgkmcnt(3)
	v_add_f32_e32 v40, v40, v44
	s_waitcnt lgkmcnt(2)
	v_add_f32_e32 v41, v41, v45
	s_waitcnt lgkmcnt(1)
	v_add_f32_e32 v42, v42, v46
	s_waitcnt lgkmcnt(0)
	v_add_f32_e32 v43, v43, v47
	ds_swizzle_b32 v44, v40 offset:swizzle(SWAP,4)
	ds_swizzle_b32 v45, v41 offset:swizzle(SWAP,4)
	ds_swizzle_b32 v46, v42 offset:swizzle(SWAP,4)
	ds_swizzle_b32 v47, v43 offset:swizzle(SWAP,4)
	s_waitcnt lgkmcnt(3)
	v_add_f32_e32 v40, v40, v44
	s_waitcnt lgkmcnt(2)
	v_add_f32_e32 v41, v41, v45
	s_waitcnt lgkmcnt(1)
	v_add_f32_e32 v42, v42, v46
	s_waitcnt lgkmcnt(0)
	v_add_f32_e32 v43, v43, v47
	ds_swizzle_b32 v44, v40 offset:swizzle(SWAP,8)
	ds_swizzle_b32 v45, v41 offset:swizzle(SWAP,8)
	ds_swizzle_b32 v46, v42 offset:swizzle(SWAP,8)
	ds_swizzle_b32 v47, v43 offset:swizzle(SWAP,8)
	s_waitcnt lgkmcnt(3)
	v_add_f32_e32 v40, v40, v44
	s_waitcnt lgkmcnt(2)
	v_add_f32_e32 v41, v41, v45
	s_waitcnt lgkmcnt(1)
	v_add_f32_e32 v42, v42, v46
	s_waitcnt lgkmcnt(0)
	v_add_f32_e32 v43, v43, v47
	ds_swizzle_b32 v44, v40 offset:swizzle(SWAP,16)
	ds_swizzle_b32 v45, v41 offset:swizzle(SWAP,16)
	ds_swizzle_b32 v46, v42 offset:swizzle(SWAP,16)
	ds_swizzle_b32 v47, v43 offset:swizzle(SWAP,16)
	s_waitcnt lgkmcnt(3)
	v_add_f32_e32 v40, v40, v44
	s_waitcnt lgkmcnt(2)
	v_add_f32_e32 v41, v41, v45
	s_waitcnt lgkmcnt(1)
	v_add_f32_e32 v42, v42, v46
	s_waitcnt lgkmcnt(0)
	v_add_f32_e32 v43, v43, v47
	v_mov_b32_e32 v44, v40
	v_mov_b32_e32 v45, v41
	v_mov_b32_e32 v46, v42
	v_mov_b32_e32 v47, v43
	s_nop 1
	v_permlane32_swap_b32_e32 v40, v44
	v_permlane32_swap_b32_e32 v41, v45
	v_permlane32_swap_b32_e32 v42, v46
	v_permlane32_swap_b32_e32 v43, v47
	s_and_saveexec_b64 s[14:15], s[6:7]
	v_add_f32_e32 v40, v40, v44
	v_add_f32_e32 v41, v41, v45
	v_add_f32_e32 v42, v42, v46
	v_add_f32_e32 v43, v43, v47
	v_fmamk_f32 v40, v40, 0x3a800000, v200
	v_fmamk_f32 v41, v41, 0x3a800000, v200
	v_fmamk_f32 v42, v42, 0x3a800000, v200
	v_fmamk_f32 v43, v43, 0x3a800000, v200
	v_rsq_f32_e32 v40, v40
	v_rsq_f32_e32 v41, v41
	v_rsq_f32_e32 v42, v42
	v_rsq_f32_e32 v43, v43
	s_lshl_b32 s10, s8, 2
	s_add_u32 s10, s0, s10
	s_addc_u32 s11, s13, 0
	global_store_dword v1, v40, s[10:11]
	s_add_u32 s10, s10, 0x2000
	s_addc_u32 s11, s11, 0
	global_store_dword v1, v41, s[10:11]
	s_add_u32 s10, s10, 0x2000
	s_addc_u32 s11, s11, 0
	global_store_dword v1, v42, s[10:11]
	s_add_u32 s10, s10, 0x2000
	s_addc_u32 s11, s11, 0
	global_store_dword v1, v43, s[10:11]
	s_or_b64 exec, exec, s[14:15]
	s_addk_i32 s8, 0x2000
	s_cmp_lt_i32 s8, 0x10000
	s_cbranch_scc1 .Lrs4_loop
; __device__ __forceinline__ void rstd_rows(const bf16_t* __restrict__ Hb, float* __restrict__ rs, int nrows, int gw, int NGW, int lane) {
;     for (int m = gw; m < nrows; m += 2 * NGW) {
;         const int m2 = m + NGW; const bool has2 = m2 < nrows;
;         const u32x4* p0 = (const u32x4*)(Hb + (size_t)m * DMODEL) + lane; const u32x4* p1 = (const u32x4*)(Hb + (size_t)(has2 ? m2 : m) * DMODEL) + lane;
;         const u32x4 a0 = p0[0], a1 = p0[64], b0 = p1[0], b1 = p1[64];
;         float s0 = 0.f, s1 = 0.f;
; #pragma unroll
;         for (int k = 0; k < 4; ++k) { float x, y;
;             x = __uint_as_float(a0[k] << 16); y = __uint_as_float(a0[k] & 0xffff0000u); s0 += x * x + y * y;
;             x = __uint_as_float(a1[k] << 16); y = __uint_as_float(a1[k] & 0xffff0000u); s0 += x * x + y * y;
;             x = __uint_as_float(b0[k] << 16); y = __uint_as_float(b0[k] & 0xffff0000u); s1 += x * x + y * y;
;             x = __uint_as_float(b1[k] << 16); y = __uint_as_float(b1[k] & 0xffff0000u); s1 += x * x + y * y; }
;         s0 = wave_sum(s0); s1 = wave_sum(s1);
;         if (lane == 0) { rs[m] = rsqrtf(s0 * (1.0f / DMODEL) + EPS); if (has2) rs[m2] = rsqrtf(s1 * (1.0f / DMODEL) + EPS); }
;     }
; }
	s_add_i32 s16, s8, 0x2000
	s_lshl_b32 s10, s16, 11
	s_mov_b32 s11, 0
	v_lshl_add_u64 v[28:29], v[2:3], 0, s[10:11]
	global_load_dwordx4 v[48:51], v[28:29], off
	global_load_dwordx4 v[52:55], v[28:29], off offset:1024
	v_lshl_add_u64 v[38:39], v[28:29], 0, s[100:101]
	global_load_dwordx4 v[56:59], v[38:39], off
	global_load_dwordx4 v[60:63], v[38:39], off offset:1024
	v_lshl_add_u64 v[28:29], v[38:39], 0, s[100:101]
	global_load_dwordx4 v[64:67], v[28:29], off
	global_load_dwordx4 v[68:71], v[28:29], off offset:1024
	v_lshl_add_u64 v[38:39], v[28:29], 0, s[100:101]
	global_load_dwordx4 v[72:75], v[38:39], off
	global_load_dwordx4 v[76:79], v[38:39], off offset:1024
	s_waitcnt vmcnt(14)
	v_lshlrev_b32_e32 v44, 16, v4
	v_and_b32_e32 v4, 0xffff0000, v4
	v_mul_f32_e32 v40, v44, v44
	v_fmac_f32_e32 v40, v4, v4
	v_lshlrev_b32_e32 v44, 16, v5
	v_and_b32_e32 v5, 0xffff0000, v5
	v_fmac_f32_e32 v40, v44, v44
	v_fmac_f32_e32 v40, v5, v5
	v_lshlrev_b32_e32 v44, 16, v6
	v_and_b32_e32 v6, 0xffff0000, v6
	v_fmac_f32_e32 v40, v44, v44
	v_fmac_f32_e32 v40, v6, v6
	v_lshlrev_b32_e32 v44, 16, v7
	v_and_b32_e32 v7, 0xffff0000, v7
	v_fmac_f32_e32 v40, v44, v44
	v_fmac_f32_e32 v40, v7, v7
	v_lshlrev_b32_e32 v44, 16, v8
	v_and_b32_e32 v8, 0xffff0000, v8
	v_fmac_f32_e32 v40, v44, v44
	v_fmac_f32_e32 v40, v8, v8
	v_lshlrev_b32_e32 v44, 16, v9
	v_and_b32_e32 v9, 0xffff0000, v9
	v_fmac_f32_e32 v40, v44, v44
	v_fmac_f32_e32 v40, v9, v9
	v_lshlrev_b32_e32 v44, 16, v10
	v_and_b32_e32 v10, 0xffff0000, v10
	v_fmac_f32_e32 v40, v44, v44
	v_fmac_f32_e32 v40, v10, v10
	v_lshlrev_b32_e32 v44, 16, v11
	v_and_b32_e32 v11, 0xffff0000, v11
	v_fmac_f32_e32 v40, v44, v44
	v_fmac_f32_e32 v40, v11, v11
	s_waitcnt vmcnt(12)
	v_lshlrev_b32_e32 v44, 16, v12
	v_and_b32_e32 v12, 0xffff0000, v12
	v_mul_f32_e32 v41, v44, v44
	v_fmac_f32_e32 v41, v12, v12
	v_lshlrev_b32_e32 v44, 16, v13
	v_and_b32_e32 v13, 0xffff0000, v13
	v_fmac_f32_e32 v41, v44, v44
	v_fmac_f32_e32 v41, v13, v13
	v_lshlrev_b32_e32 v44, 16, v14
	v_and_b32_e32 v14, 0xffff0000, v14
	v_fmac_f32_e32 v41, v44, v44
	v_fmac_f32_e32 v41, v14, v14
	v_lshlrev_b32_e32 v44, 16, v15
	v_and_b32_e32 v15, 0xffff0000, v15
	v_fmac_f32_e32 v41, v44, v44
	v_fmac_f32_e32 v41, v15, v15
	v_lshlrev_b32_e32 v44, 16, v16
	v_and_b32_e32 v16, 0xffff0000, v16
	v_fmac_f32_e32 v41, v44, v44
	v_fmac_f32_e32 v41, v16, v16
	v_lshlrev_b32_e32 v44, 16, v17
	v_and_b32_e32 v17, 0xffff0000, v17
	v_fmac_f32_e32 v41, v44, v44
	v_fmac_f32_e32 v41, v17, v17
	v_lshlrev_b32_e32 v44, 16, v18
	v_and_b32_e32 v18, 0xffff0000, v18
	v_fmac_f32_e32 v41, v44, v44
	v_fmac_f32_e32 v41, v18, v18
	v_lshlrev_b32_e32 v44, 16, v19
	v_and_b32_e32 v19, 0xffff0000, v19
	v_fmac_f32_e32 v41, v44, v44
	v_fmac_f32_e32 v41, v19, v19
	s_waitcnt vmcnt(10)
	v_lshlrev_b32_e32 v44, 16, v20
	v_and_b32_e32 v20, 0xffff0000, v20
	v_mul_f32_e32 v42, v44, v44
	v_fmac_f32_e32 v42, v20, v20
	v_lshlrev_b32_e32 v44, 16, v21
	v_and_b32_e32 v21, 0xffff0000, v21
	v_fmac_f32_e32 v42, v44, v44
	v_fmac_f32_e32 v42, v21, v21
	v_lshlrev_b32_e32 v44, 16, v22
	v_and_b32_e32 v22, 0xffff0000, v22
	v_fmac_f32_e32 v42, v44, v44
	v_fmac_f32_e32 v42, v22, v22
	v_lshlrev_b32_e32 v44, 16, v23
	v_and_b32_e32 v23, 0xffff0000, v23
	v_fmac_f32_e32 v42, v44, v44
	v_fmac_f32_e32 v42, v23, v23
	v_lshlrev_b32_e32 v44, 16, v24
	v_and_b32_e32 v24, 0xffff0000, v24
	v_fmac_f32_e32 v42, v44, v44
	v_fmac_f32_e32 v42, v24, v24
	v_lshlrev_b32_e32 v44, 16, v25
	v_and_b32_e32 v25, 0xffff0000, v25
	v_fmac_f32_e32 v42, v44, v44
	v_fmac_f32_e32 v42, v25, v25
	v_lshlrev_b32_e32 v44, 16, v26
	v_and_b32_e32 v26, 0xffff0000, v26
	v_fmac_f32_e32 v42, v44, v44
	v_fmac_f32_e32 v42, v26, v26
	v_lshlrev_b32_e32 v44, 16, v27
	v_and_b32_e32 v27, 0xffff0000, v27
	v_fmac_f32_e32 v42, v44, v44
	v_fmac_f32_e32 v42, v27, v27
	s_waitcnt vmcnt(8)
	v_lshlrev_b32_e32 v44, 16, v30
	v_and_b32_e32 v30, 0xffff0000, v30
	v_mul_f32_e32 v43, v44, v44
	v_fmac_f32_e32 v43, v30, v30
	v_lshlrev_b32_e32 v44, 16, v31
	v_and_b32_e32 v31, 0xffff0000, v31
	v_fmac_f32_e32 v43, v44, v44
	v_fmac_f32_e32 v43, v31, v31
	v_lshlrev_b32_e32 v44, 16, v32
	v_and_b32_e32 v32, 0xffff0000, v32
	v_fmac_f32_e32 v43, v44, v44
	v_fmac_f32_e32 v43, v32, v32
	v_lshlrev_b32_e32 v44, 16, v33
	v_and_b32_e32 v33, 0xffff0000, v33
	v_fmac_f32_e32 v43, v44, v44
	v_fmac_f32_e32 v43, v33, v33
	v_lshlrev_b32_e32 v44, 16, v34
	v_and_b32_e32 v34, 0xffff0000, v34
	v_fmac_f32_e32 v43, v44, v44
	v_fmac_f32_e32 v43, v34, v34
	v_lshlrev_b32_e32 v44, 16, v35
	v_and_b32_e32 v35, 0xffff0000, v35
	v_fmac_f32_e32 v43, v44, v44
	v_fmac_f32_e32 v43, v35, v35
	v_lshlrev_b32_e32 v44, 16, v36
	v_and_b32_e32 v36, 0xffff0000, v36
	v_fmac_f32_e32 v43, v44, v44
	v_fmac_f32_e32 v43, v36, v36
	v_lshlrev_b32_e32 v44, 16, v37
	v_and_b32_e32 v37, 0xffff0000, v37
	v_fmac_f32_e32 v43, v44, v44
	v_fmac_f32_e32 v43, v37, v37
	ds_swizzle_b32 v44, v40 offset:swizzle(SWAP,1)
	ds_swizzle_b32 v45, v41 offset:swizzle(SWAP,1)
	ds_swizzle_b32 v46, v42 offset:swizzle(SWAP,1)
	ds_swizzle_b32 v47, v43 offset:swizzle(SWAP,1)
	s_waitcnt lgkmcnt(3)
	v_add_f32_e32 v40, v40, v44
	s_waitcnt lgkmcnt(2)
	v_add_f32_e32 v41, v41, v45
	s_waitcnt lgkmcnt(1)
	v_add_f32_e32 v42, v42, v46
	s_waitcnt lgkmcnt(0)
	v_add_f32_e32 v43, v43, v47
	ds_swizzle_b32 v44, v40 offset:swizzle(SWAP,2)
	ds_swizzle_b32 v45, v41 offset:swizzle(SWAP,2)
	ds_swizzle_b32 v46, v42 offset:swizzle(SWAP,2)
	ds_swizzle_b32 v47, v43 offset:swizzle(SWAP,2)
	s_waitcnt lgkmcnt(3)
	v_add_f32_e32 v40, v40, v44
	s_waitcnt lgkmcnt(2)
	v_add_f32_e32 v41, v41, v45
	s_waitcnt lgkmcnt(1)
	v_add_f32_e32 v42, v42, v46
	s_waitcnt lgkmcnt(0)
; __device__ __forceinline__ void rstd_rows(const bf16_t* __restrict__ Hb, float* __restrict__ rs, int nrows, int gw, int NGW, int lane) {
;     for (int m = gw; m < nrows; m += 2 * NGW) {
;         const int m2 = m + NGW; const bool has2 = m2 < nrows;
;         const u32x4* p0 = (const u32x4*)(Hb + (size_t)m * DMODEL) + lane; const u32x4* p1 = (const u32x4*)(Hb + (size_t)(has2 ? m2 : m) * DMODEL) + lane;
;         const u32x4 a0 = p0[0], a1 = p0[64], b0 = p1[0], b1 = p1[64];
;         float s0 = 0.f, s1 = 0.f;
; #pragma unroll
;         for (int k = 0; k < 4; ++k) { float x, y;
;             x = __uint_as_float(a0[k] << 16); y = __uint_as_float(a0[k] & 0xffff0000u); s0 += x * x + y * y;
;             x = __uint_as_float(a1[k] << 16); y = __uint_as_float(a1[k] & 0xffff0000u); s0 += x * x + y * y;
;             x = __uint_as_float(b0[k] << 16); y = __uint_as_float(b0[k] & 0xffff0000u); s1 += x * x + y * y;
;             x = __uint_as_float(b1[k] << 16); y = __uint_as_float(b1[k] & 0xffff0000u); s1 += x * x + y * y; }
;         s0 = wave_sum(s0); s1 = wave_sum(s1);
;         if (lane == 0) { rs[m] = rsqrtf(s0 * (1.0f / DMODEL) + EPS); if (has2) rs[m2] = rsqrtf(s1 * (1.0f / DMODEL) + EPS); }
;     }
; }
	v_add_f32_e32 v43, v43, v47
	ds_swizzle_b32 v44, v40 offset:swizzle(SWAP,4)
	ds_swizzle_b32 v45, v41 offset:swizzle(SWAP,4)
	ds_swizzle_b32 v46, v42 offset:swizzle(SWAP,4)
	ds_swizzle_b32 v47, v43 offset:swizzle(SWAP,4)
	s_waitcnt lgkmcnt(3)
	v_add_f32_e32 v40, v40, v44
	s_waitcnt lgkmcnt(2)
	v_add_f32_e32 v41, v41, v45
	s_waitcnt lgkmcnt(1)
	v_add_f32_e32 v42, v42, v46
	s_waitcnt lgkmcnt(0)
	v_add_f32_e32 v43, v43, v47
	ds_swizzle_b32 v44, v40 offset:swizzle(SWAP,8)
	ds_swizzle_b32 v45, v41 offset:swizzle(SWAP,8)
	ds_swizzle_b32 v46, v42 offset:swizzle(SWAP,8)
	ds_swizzle_b32 v47, v43 offset:swizzle(SWAP,8)
	s_waitcnt lgkmcnt(3)
	v_add_f32_e32 v40, v40, v44
	s_waitcnt lgkmcnt(2)
	v_add_f32_e32 v41, v41, v45
	s_waitcnt lgkmcnt(1)
	v_add_f32_e32 v42, v42, v46
	s_waitcnt lgkmcnt(0)
	v_add_f32_e32 v43, v43, v47
	ds_swizzle_b32 v44, v40 offset:swizzle(SWAP,16)
	ds_swizzle_b32 v45, v41 offset:swizzle(SWAP,16)
	ds_swizzle_b32 v46, v42 offset:swizzle(SWAP,16)
	ds_swizzle_b32 v47, v43 offset:swizzle(SWAP,16)
	s_waitcnt lgkmcnt(3)
	v_add_f32_e32 v40, v40, v44
	s_waitcnt lgkmcnt(2)
	v_add_f32_e32 v41, v41, v45
	s_waitcnt lgkmcnt(1)
	v_add_f32_e32 v42, v42, v46
	s_waitcnt lgkmcnt(0)
	v_add_f32_e32 v43, v43, v47
	v_mov_b32_e32 v44, v40
	v_mov_b32_e32 v45, v41
	v_mov_b32_e32 v46, v42
	v_mov_b32_e32 v47, v43
	s_nop 1
	v_permlane32_swap_b32_e32 v40, v44
	v_permlane32_swap_b32_e32 v41, v45
	v_permlane32_swap_b32_e32 v42, v46
	v_permlane32_swap_b32_e32 v43, v47
	s_and_saveexec_b64 s[14:15], s[6:7]
	v_add_f32_e32 v40, v40, v44
	v_add_f32_e32 v41, v41, v45
	v_add_f32_e32 v42, v42, v46
	v_add_f32_e32 v43, v43, v47
	v_fmamk_f32 v40, v40, 0x3a800000, v200
	v_fmamk_f32 v41, v41, 0x3a800000, v200
	v_fmamk_f32 v42, v42, 0x3a800000, v200
	v_fmamk_f32 v43, v43, 0x3a800000, v200
	v_rsq_f32_e32 v40, v40
	v_rsq_f32_e32 v41, v41
	v_rsq_f32_e32 v42, v42
	v_rsq_f32_e32 v43, v43
	s_lshl_b32 s10, s8, 2
	s_add_u32 s10, s0, s10
	s_addc_u32 s11, s13, 0
	global_store_dword v1, v40, s[10:11]
	s_add_u32 s10, s10, 0x2000
	s_addc_u32 s11, s11, 0
	global_store_dword v1, v41, s[10:11]
	s_add_u32 s10, s10, 0x2000
	s_addc_u32 s11, s11, 0
	global_store_dword v1, v42, s[10:11]
	s_add_u32 s10, s10, 0x2000
	s_addc_u32 s11, s11, 0
	global_store_dword v1, v43, s[10:11]
	s_or_b64 exec, exec, s[14:15]
	s_addk_i32 s8, 0x2000
	s_waitcnt vmcnt(6)
	v_lshlrev_b32_e32 v44, 16, v48
	v_and_b32_e32 v48, 0xffff0000, v48
	v_mul_f32_e32 v40, v44, v44
	v_fmac_f32_e32 v40, v48, v48
	v_lshlrev_b32_e32 v44, 16, v49
	v_and_b32_e32 v49, 0xffff0000, v49
	v_fmac_f32_e32 v40, v44, v44
	v_fmac_f32_e32 v40, v49, v49
	v_lshlrev_b32_e32 v44, 16, v50
	v_and_b32_e32 v50, 0xffff0000, v50
	v_fmac_f32_e32 v40, v44, v44
	v_fmac_f32_e32 v40, v50, v50
	v_lshlrev_b32_e32 v44, 16, v51
	v_and_b32_e32 v51, 0xffff0000, v51
	v_fmac_f32_e32 v40, v44, v44
	v_fmac_f32_e32 v40, v51, v51
	v_lshlrev_b32_e32 v44, 16, v52
	v_and_b32_e32 v52, 0xffff0000, v52
	v_fmac_f32_e32 v40, v44, v44
	v_fmac_f32_e32 v40, v52, v52
	v_lshlrev_b32_e32 v44, 16, v53
	v_and_b32_e32 v53, 0xffff0000, v53
	v_fmac_f32_e32 v40, v44, v44
	v_fmac_f32_e32 v40, v53, v53
	v_lshlrev_b32_e32 v44, 16, v54
	v_and_b32_e32 v54, 0xffff0000, v54
	v_fmac_f32_e32 v40, v44, v44
	v_fmac_f32_e32 v40, v54, v54
	v_lshlrev_b32_e32 v44, 16, v55
	v_and_b32_e32 v55, 0xffff0000, v55
	v_fmac_f32_e32 v40, v44, v44
	v_fmac_f32_e32 v40, v55, v55
	s_waitcnt vmcnt(4)
	v_lshlrev_b32_e32 v44, 16, v56
	v_and_b32_e32 v56, 0xffff0000, v56
	v_mul_f32_e32 v41, v44, v44
	v_fmac_f32_e32 v41, v56, v56
	v_lshlrev_b32_e32 v44, 16, v57
	v_and_b32_e32 v57, 0xffff0000, v57
	v_fmac_f32_e32 v41, v44, v44
	v_fmac_f32_e32 v41, v57, v57
	v_lshlrev_b32_e32 v44, 16, v58
	v_and_b32_e32 v58, 0xffff0000, v58
	v_fmac_f32_e32 v41, v44, v44
	v_fmac_f32_e32 v41, v58, v58
	v_lshlrev_b32_e32 v44, 16, v59
	v_and_b32_e32 v59, 0xffff0000, v59
	v_fmac_f32_e32 v41, v44, v44
	v_fmac_f32_e32 v41, v59, v59
	v_lshlrev_b32_e32 v44, 16, v60
	v_and_b32_e32 v60, 0xffff0000, v60
	v_fmac_f32_e32 v41, v44, v44
	v_fmac_f32_e32 v41, v60, v60
	v_lshlrev_b32_e32 v44, 16, v61
	v_and_b32_e32 v61, 0xffff0000, v61
	v_fmac_f32_e32 v41, v44, v44
	v_fmac_f32_e32 v41, v61, v61
	v_lshlrev_b32_e32 v44, 16, v62
	v_and_b32_e32 v62, 0xffff0000, v62
	v_fmac_f32_e32 v41, v44, v44
	v_fmac_f32_e32 v41, v62, v62
	v_lshlrev_b32_e32 v44, 16, v63
	v_and_b32_e32 v63, 0xffff0000, v63
	v_fmac_f32_e32 v41, v44, v44
	v_fmac_f32_e32 v41, v63, v63
	s_waitcnt vmcnt(2)
; __device__ __forceinline__ void rstd_rows(const bf16_t* __restrict__ Hb, float* __restrict__ rs, int nrows, int gw, int NGW, int lane) {
;     for (int m = gw; m < nrows; m += 2 * NGW) {
;         const int m2 = m + NGW; const bool has2 = m2 < nrows;
;         const u32x4* p0 = (const u32x4*)(Hb + (size_t)m * DMODEL) + lane; const u32x4* p1 = (const u32x4*)(Hb + (size_t)(has2 ? m2 : m) * DMODEL) + lane;
;         const u32x4 a0 = p0[0], a1 = p0[64], b0 = p1[0], b1 = p1[64];
;         float s0 = 0.f, s1 = 0.f;
; #pragma unroll
;         for (int k = 0; k < 4; ++k) { float x, y;
;             x = __uint_as_float(a0[k] << 16); y = __uint_as_float(a0[k] & 0xffff0000u); s0 += x * x + y * y;
;             x = __uint_as_float(a1[k] << 16); y = __uint_as_float(a1[k] & 0xffff0000u); s0 += x * x + y * y;
;             x = __uint_as_float(b0[k] << 16); y = __uint_as_float(b0[k] & 0xffff0000u); s1 += x * x + y * y;
;             x = __uint_as_float(b1[k] << 16); y = __uint_as_float(b1[k] & 0xffff0000u); s1 += x * x + y * y; }
;         s0 = wave_sum(s0); s1 = wave_sum(s1);
;         if (lane == 0) { rs[m] = rsqrtf(s0 * (1.0f / DMODEL) + EPS); if (has2) rs[m2] = rsqrtf(s1 * (1.0f / DMODEL) + EPS); }
;     }
; }
	v_lshlrev_b32_e32 v44, 16, v64
	v_and_b32_e32 v64, 0xffff0000, v64
	v_mul_f32_e32 v42, v44, v44
	v_fmac_f32_e32 v42, v64, v64
	v_lshlrev_b32_e32 v44, 16, v65
	v_and_b32_e32 v65, 0xffff0000, v65
	v_fmac_f32_e32 v42, v44, v44
	v_fmac_f32_e32 v42, v65, v65
	v_lshlrev_b32_e32 v44, 16, v66
	v_and_b32_e32 v66, 0xffff0000, v66
	v_fmac_f32_e32 v42, v44, v44
	v_fmac_f32_e32 v42, v66, v66
	v_lshlrev_b32_e32 v44, 16, v67
	v_and_b32_e32 v67, 0xffff0000, v67
	v_fmac_f32_e32 v42, v44, v44
	v_fmac_f32_e32 v42, v67, v67
	v_lshlrev_b32_e32 v44, 16, v68
	v_and_b32_e32 v68, 0xffff0000, v68
	v_fmac_f32_e32 v42, v44, v44
	v_fmac_f32_e32 v42, v68, v68
	v_lshlrev_b32_e32 v44, 16, v69
	v_and_b32_e32 v69, 0xffff0000, v69
	v_fmac_f32_e32 v42, v44, v44
	v_fmac_f32_e32 v42, v69, v69
	v_lshlrev_b32_e32 v44, 16, v70
	v_and_b32_e32 v70, 0xffff0000, v70
	v_fmac_f32_e32 v42, v44, v44
	v_fmac_f32_e32 v42, v70, v70
	v_lshlrev_b32_e32 v44, 16, v71
	v_and_b32_e32 v71, 0xffff0000, v71
	v_fmac_f32_e32 v42, v44, v44
	v_fmac_f32_e32 v42, v71, v71
	s_waitcnt vmcnt(0)
	v_lshlrev_b32_e32 v44, 16, v72
	v_and_b32_e32 v72, 0xffff0000, v72
	v_mul_f32_e32 v43, v44, v44
	v_fmac_f32_e32 v43, v72, v72
	v_lshlrev_b32_e32 v44, 16, v73
	v_and_b32_e32 v73, 0xffff0000, v73
	v_fmac_f32_e32 v43, v44, v44
	v_fmac_f32_e32 v43, v73, v73
	v_lshlrev_b32_e32 v44, 16, v74
	v_and_b32_e32 v74, 0xffff0000, v74
	v_fmac_f32_e32 v43, v44, v44
	v_fmac_f32_e32 v43, v74, v74
	v_lshlrev_b32_e32 v44, 16, v75
	v_and_b32_e32 v75, 0xffff0000, v75
	v_fmac_f32_e32 v43, v44, v44
	v_fmac_f32_e32 v43, v75, v75
	v_lshlrev_b32_e32 v44, 16, v76
	v_and_b32_e32 v76, 0xffff0000, v76
	v_fmac_f32_e32 v43, v44, v44
	v_fmac_f32_e32 v43, v76, v76
	v_lshlrev_b32_e32 v44, 16, v77
	v_and_b32_e32 v77, 0xffff0000, v77
	v_fmac_f32_e32 v43, v44, v44
	v_fmac_f32_e32 v43, v77, v77
	v_lshlrev_b32_e32 v44, 16, v78
	v_and_b32_e32 v78, 0xffff0000, v78
	v_fmac_f32_e32 v43, v44, v44
	v_fmac_f32_e32 v43, v78, v78
	v_lshlrev_b32_e32 v44, 16, v79
	v_and_b32_e32 v79, 0xffff0000, v79
	v_fmac_f32_e32 v43, v44, v44
	v_fmac_f32_e32 v43, v79, v79
	ds_swizzle_b32 v44, v40 offset:swizzle(SWAP,1)
	ds_swizzle_b32 v45, v41 offset:swizzle(SWAP,1)
	ds_swizzle_b32 v46, v42 offset:swizzle(SWAP,1)
	ds_swizzle_b32 v47, v43 offset:swizzle(SWAP,1)
	s_waitcnt lgkmcnt(3)
	v_add_f32_e32 v40, v40, v44
	s_waitcnt lgkmcnt(2)
	v_add_f32_e32 v41, v41, v45
	s_waitcnt lgkmcnt(1)
	v_add_f32_e32 v42, v42, v46
	s_waitcnt lgkmcnt(0)
	v_add_f32_e32 v43, v43, v47
	ds_swizzle_b32 v44, v40 offset:swizzle(SWAP,2)
	ds_swizzle_b32 v45, v41 offset:swizzle(SWAP,2)
	ds_swizzle_b32 v46, v42 offset:swizzle(SWAP,2)
	ds_swizzle_b32 v47, v43 offset:swizzle(SWAP,2)
	s_waitcnt lgkmcnt(3)
	v_add_f32_e32 v40, v40, v44
	s_waitcnt lgkmcnt(2)
	v_add_f32_e32 v41, v41, v45
	s_waitcnt lgkmcnt(1)
	v_add_f32_e32 v42, v42, v46
	s_waitcnt lgkmcnt(0)
	v_add_f32_e32 v43, v43, v47
	ds_swizzle_b32 v44, v40 offset:swizzle(SWAP,4)
	ds_swizzle_b32 v45, v41 offset:swizzle(SWAP,4)
	ds_swizzle_b32 v46, v42 offset:swizzle(SWAP,4)
	ds_swizzle_b32 v47, v43 offset:swizzle(SWAP,4)
	s_waitcnt lgkmcnt(3)
	v_add_f32_e32 v40, v40, v44
	s_waitcnt lgkmcnt(2)
	v_add_f32_e32 v41, v41, v45
	s_waitcnt lgkmcnt(1)
	v_add_f32_e32 v42, v42, v46
	s_waitcnt lgkmcnt(0)
	v_add_f32_e32 v43, v43, v47
	ds_swizzle_b32 v44, v40 offset:swizzle(SWAP,8)
	ds_swizzle_b32 v45, v41 offset:swizzle(SWAP,8)
	ds_swizzle_b32 v46, v42 offset:swizzle(SWAP,8)
	ds_swizzle_b32 v47, v43 offset:swizzle(SWAP,8)
	s_waitcnt lgkmcnt(3)
	v_add_f32_e32 v40, v40, v44
	s_waitcnt lgkmcnt(2)
	v_add_f32_e32 v41, v41, v45
	s_waitcnt lgkmcnt(1)
	v_add_f32_e32 v42, v42, v46
	s_waitcnt lgkmcnt(0)
	v_add_f32_e32 v43, v43, v47
	ds_swizzle_b32 v44, v40 offset:swizzle(SWAP,16)
	ds_swizzle_b32 v45, v41 offset:swizzle(SWAP,16)
	ds_swizzle_b32 v46, v42 offset:swizzle(SWAP,16)
	ds_swizzle_b32 v47, v43 offset:swizzle(SWAP,16)
	s_waitcnt lgkmcnt(3)
	v_add_f32_e32 v40, v40, v44
	s_waitcnt lgkmcnt(2)
	v_add_f32_e32 v41, v41, v45
	s_waitcnt lgkmcnt(1)
	v_add_f32_e32 v42, v42, v46
	s_waitcnt lgkmcnt(0)
	v_add_f32_e32 v43, v43, v47
	v_mov_b32_e32 v44, v40
	v_mov_b32_e32 v45, v41
	v_mov_b32_e32 v46, v42
	v_mov_b32_e32 v47, v43
	s_nop 1
	v_permlane32_swap_b32_e32 v40, v44
	v_permlane32_swap_b32_e32 v41, v45
	v_permlane32_swap_b32_e32 v42, v46
	v_permlane32_swap_b32_e32 v43, v47
	s_and_saveexec_b64 s[14:15], s[6:7]
	v_add_f32_e32 v40, v40, v44
	v_add_f32_e32 v41, v41, v45
	v_add_f32_e32 v42, v42, v46
	v_add_f32_e32 v43, v43, v47
	v_fmamk_f32 v40, v40, 0x3a800000, v200
	v_fmamk_f32 v41, v41, 0x3a800000, v200
	v_fmamk_f32 v42, v42, 0x3a800000, v200
	v_fmamk_f32 v43, v43, 0x3a800000, v200
	v_rsq_f32_e32 v40, v40
	v_rsq_f32_e32 v41, v41
	v_rsq_f32_e32 v42, v42
	v_rsq_f32_e32 v43, v43
	s_lshl_b32 s10, s8, 2
	s_add_u32 s10, s0, s10
	s_addc_u32 s11, s13, 0
	global_store_dword v1, v40, s[10:11]
	s_add_u32 s10, s10, 0x2000
	s_addc_u32 s11, s11, 0
	global_store_dword v1, v41, s[10:11]
	s_add_u32 s10, s10, 0x2000
	s_addc_u32 s11, s11, 0
	global_store_dword v1, v42, s[10:11]
	s_add_u32 s10, s10, 0x2000
	s_addc_u32 s11, s11, 0
	global_store_dword v1, v43, s[10:11]
	s_or_b64 exec, exec, s[14:15]
	s_branch .LBB0_396

; __global__ void __launch_bounds__(512, 2) fwd_kernel(Args a) {
	.amdhsa_kernel _Z10fwd_kernel4Args
		.amdhsa_group_segment_fixed_size 0
		.amdhsa_private_segment_fixed_size 0
		.amdhsa_kernarg_size 496
		.amdhsa_user_sgpr_count 2
		.amdhsa_user_sgpr_dispatch_ptr 0
		.amdhsa_user_sgpr_queue_ptr 0
		.amdhsa_user_sgpr_kernarg_segment_ptr 1
		.amdhsa_user_sgpr_dispatch_id 0
		.amdhsa_user_sgpr_kernarg_preload_length 0
		.amdhsa_user_sgpr_kernarg_preload_offset 0
		.amdhsa_user_sgpr_private_segment_size 0
		.amdhsa_uses_dynamic_stack 0
		.amdhsa_enable_private_segment 0
		.amdhsa_system_sgpr_workgroup_id_x 1
		.amdhsa_system_sgpr_workgroup_id_y 0
		.amdhsa_system_sgpr_workgroup_id_z 0
		.amdhsa_system_sgpr_workgroup_info 0
		.amdhsa_system_vgpr_workitem_id 2
		.amdhsa_next_free_vgpr 253
		.amdhsa_next_free_sgpr 102
		.amdhsa_accum_offset 256
		.amdhsa_reserve_vcc 1
		.amdhsa_float_round_mode_32 0
		.amdhsa_float_round_mode_16_64 0
		.amdhsa_float_denorm_mode_32 3
		.amdhsa_float_denorm_mode_16_64 3
		.amdhsa_dx10_clamp 1
		.amdhsa_ieee_mode 1
		.amdhsa_fp16_overflow 0
		.amdhsa_tg_split 0
		.amdhsa_exception_fp_ieee_invalid_op 0
		.amdhsa_exception_fp_denorm_src 0
		.amdhsa_exception_fp_ieee_div_zero 0
		.amdhsa_exception_fp_ieee_overflow 0
		.amdhsa_exception_fp_ieee_underflow 0
		.amdhsa_exception_fp_ieee_inexact 0
		.amdhsa_exception_int_div_zero 0
	.end_amdhsa_kernel

; __global__ void __launch_bounds__(512, 2) fwd_kernel(Args a) {
amdhsa.kernels:
  - .agpr_count:     0
    .args:
      - .offset:         0
        .size:           240
        .value_kind:     by_value
      - .offset:         240
        .size:           4
        .value_kind:     hidden_block_count_x
      - .offset:         244
        .size:           4
        .value_kind:     hidden_block_count_y
      - .offset:         248
        .size:           4
        .value_kind:     hidden_block_count_z
      - .offset:         252
        .size:           2
        .value_kind:     hidden_group_size_x
      - .offset:         254
        .size:           2
        .value_kind:     hidden_group_size_y
      - .offset:         256
        .size:           2
        .value_kind:     hidden_group_size_z
      - .offset:         258
        .size:           2
        .value_kind:     hidden_remainder_x
      - .offset:         260
        .size:           2
        .value_kind:     hidden_remainder_y
      - .offset:         262
        .size:           2
        .value_kind:     hidden_remainder_z
      - .offset:         280
        .size:           8
        .value_kind:     hidden_global_offset_x
      - .offset:         288
        .size:           8
        .value_kind:     hidden_global_offset_y
      - .offset:         296
        .size:           8
        .value_kind:     hidden_global_offset_z
      - .offset:         304
        .size:           2
        .value_kind:     hidden_grid_dims
      - .offset:         328
        .size:           8
        .value_kind:     hidden_multigrid_sync_arg
      - .offset:         360
        .size:           4
        .value_kind:     hidden_dynamic_lds_size
    .group_segment_fixed_size: 0
    .kernarg_segment_align: 8
    .kernarg_segment_size: 496
    .language:       OpenCL C
    .language_version:
      - 2
      - 0
    .max_flat_workgroup_size: 512
    .name:           _Z10fwd_kernel4Args
    .private_segment_fixed_size: 0
    .sgpr_count:     108
    .sgpr_spill_count: 65
    .symbol:         _Z10fwd_kernel4Args.kd
    .uniform_work_group_size: 1
    .uses_dynamic_stack: false
    .vgpr_count:     253
    .vgpr_spill_count: 0
    .wavefront_size: 64
